# rotated P2 unit order combined with poll loops that do not sleep between polls
# speedup vs baseline: 1.0056x; 1.0004x over previous
.Lp1_spin:
	global_load_dword v2, v1, s[24:25] sc1
	s_waitcnt vmcnt(0)
	v_readfirstlane_b32 s9, v2
	s_nop 0
	s_cmpk_gt_u32 s9, 0xff
	s_cbranch_scc1 .LBB0_117
	s_sleep 0
	s_add_i32 s8, s8, 1
	s_cmp_lt_u32 s8, 0x20000
	s_cbranch_scc1 .Lp1_spin

.LBB0_131:
	global_load_dword v16, v17, s[24:25] offset:1024 sc1
	global_load_dword v1, v17, s[24:25] offset:1280 sc1
	global_load_dword v2, v17, s[24:25] offset:1536 sc1
	global_load_dword v3, v17, s[24:25] offset:1792 sc1
	global_load_dword v4, v17, s[24:25] offset:2048 sc1
	global_load_dword v5, v17, s[24:25] offset:2304 sc1
	global_load_dword v6, v17, s[24:25] offset:2560 sc1
	global_load_dword v7, v17, s[24:25] offset:2816 sc1
	global_load_dword v8, v17, s[24:25] offset:3072 sc1
	global_load_dword v9, v17, s[24:25] offset:3328 sc1
	global_load_dword v10, v17, s[24:25] offset:3584 sc1
	global_load_dword v11, v17, s[24:25] offset:3840 sc1
	global_load_dword v12, v17, s[8:9] sc1
	global_load_dword v13, v17, s[10:11] sc1
	global_load_dword v14, v17, s[12:13] sc1
	global_load_dword v15, v17, s[14:15] sc1
	s_mov_b64 s[16:17], -1
	s_mov_b64 s[18:19], -1
	s_waitcnt vmcnt(14)
	v_add_u32_e32 v18, v1, v16
	s_waitcnt vmcnt(13)
	v_add_u32_e32 v18, v18, v2
	s_waitcnt vmcnt(12)
	v_add_u32_e32 v18, v18, v3
	s_waitcnt vmcnt(11)
	v_add_u32_e32 v18, v18, v4
	s_waitcnt vmcnt(10)
	v_add_u32_e32 v18, v18, v5
	s_waitcnt vmcnt(9)
	v_add_u32_e32 v18, v18, v6
	s_waitcnt vmcnt(8)
	v_add_u32_e32 v18, v18, v7
	s_waitcnt vmcnt(7)
	v_add_u32_e32 v18, v18, v8
	s_waitcnt vmcnt(6)
	v_add_u32_e32 v18, v18, v9
	s_waitcnt vmcnt(5)
	v_add_u32_e32 v18, v18, v10
	s_waitcnt vmcnt(4)
	v_add_u32_e32 v18, v18, v11
	s_waitcnt vmcnt(3)
	v_add_u32_e32 v18, v18, v12
	s_waitcnt vmcnt(2)
	v_add_u32_e32 v18, v18, v13
	s_waitcnt vmcnt(1)
	v_add_u32_e32 v18, v18, v14
	s_waitcnt vmcnt(0)
	v_add_u32_e32 v18, v18, v15
	v_cmp_eq_u32_e32 vcc, s22, v18
	s_cbranch_vccnz .LBB0_130
	s_and_b32 s16, s23, 0xff
	s_cmp_eq_u32 s16, 0
	s_mov_b64 s[16:17], -1
	s_mov_b64 s[20:21], -1
	s_sleep 0
	s_cbranch_scc1 .LBB0_135
	s_and_b64 vcc, exec, s[20:21]
	s_cbranch_vccz .LBB0_130

.LBB0_147:
	s_and_b32 s22, s34, 0xff
	s_mov_b64 s[20:21], -1
	s_cmp_lg_u32 s22, 0
	s_mov_b64 s[30:31], -1
	s_sleep 0
	s_cbranch_scc0 .LBB0_150
	s_and_b64 vcc, exec, s[30:31]
	s_cbranch_vccz .LBB0_146

.LBB0_164:
	s_and_b32 s22, s36, 0xff
	s_cmp_lg_u32 s22, 0
	s_mov_b64 s[30:31], -1
	s_sleep 0
	s_cbranch_scc0 .LBB0_167
	s_mov_b64 s[34:35], -1
	s_and_b64 vcc, exec, s[30:31]
	s_cbranch_vccz .LBB0_163

.Lpg_spin:
	global_load_dword v2, v1, s[24:25] sc1
	s_waitcnt vmcnt(0)
	v_readfirstlane_b32 s66, v2
	s_nop 3
	s_cmp_ge_u32 s66, 2
	s_cbranch_scc1 .Lpg_done
	s_sleep 0
	s_add_i32 s67, s67, 1
	s_cmp_lt_u32 s67, 0x40000
	s_cbranch_scc1 .Lpg_spin

.LBB0_497:
	s_sleep 0
	s_cbranch_execz .LBB0_500

.Lpb_spin:
	global_load_dword v4, v1, s[24:25] sc1
	global_load_dword v5, v3, s[24:25] sc1
	s_waitcnt vmcnt(0)
	v_readfirstlane_b32 s10, v4
	v_readfirstlane_b32 s11, v5
	s_nop 3
	s_and_b32 s12, s10, 0xff
	s_cmp_ge_u32 s12, 8
	s_cselect_b32 s12, 1, 0
	s_cmp_ge_u32 s11, 8
	s_cselect_b32 s13, 1, 0
	s_and_b32 s12, s12, s13
	s_cmp_lg_u32 s12, 0
	s_cbranch_scc1 .Lpb_done
	s_sleep 0
	s_add_i32 s14, s14, 1
	s_cmp_lt_u32 s14, 0x40000
	s_cbranch_scc1 .Lpb_spin

.Lpb_spin2:
	global_load_dword v4, v1, s[24:25] sc1
	s_waitcnt vmcnt(0)
	v_readfirstlane_b32 s10, v4
	s_nop 3
	s_cmp_ge_u32 s10, 8
	s_cbranch_scc1 .Lpb_done2
	s_sleep 0
	s_add_i32 s14, s14, 1
	s_cmp_lt_u32 s14, 0x40000
	s_cbranch_scc1 .Lpb_spin2
